# grid barrier: the L1 invalidate is issued when the workgroup arrives (XCD-last: together with the L2 write-back) instead of after the release is observed; no wave of the workgroup issues loads in betw
# speedup vs baseline: 1.0144x; 1.0084x over previous
; __device__ __forceinline__ unsigned xb_ld(unsigned* p)              { return __hip_atomic_load(p, __ATOMIC_RELAXED, __HIP_MEMORY_SCOPE_AGENT); }
; __device__ __forceinline__ unsigned xb_add(unsigned* p, unsigned v) { return __hip_atomic_fetch_add(p, v, __ATOMIC_RELAXED, __HIP_MEMORY_SCOPE_AGENT); }
; #define XB_SPIN(cond, bar) do { unsigned _sp = 0; while (cond) { __builtin_amdgcn_s_sleep(1); \
;     if ((++_sp & 255u) == 0u) { if (xb_ld(&(bar)[XB_TMO])) break; if (_sp > XB_SPIN_CAP) { atomicAdd(&(bar)[XB_TMO], 1u); break; } } } } while (0)
; __device__ __forceinline__ void xcd_barrier(const XcdBarrier& b) {
;     ...
;         unsigned nloc = b.st[0], nx = b.st[1];
;         if (nloc == 0u) { xcd_barrier_complete(bar, b.x, nloc, nx); b.st[0] = nloc; b.st[1] = nx; }
;         const unsigned old = xb_add(&bar[XB_XSUB(b.x)], 1u);
;         const unsigned gen = old / nloc;
;         if (old + 1u == (gen + 1u) * nloc) {
;             __builtin_amdgcn_fence(__ATOMIC_RELEASE, "agent");
;             asm volatile("s_waitcnt vmcnt(0)" ::: "memory");
;             const unsigned og = xb_add(&bar[XB_TOP], 1u);
;             const unsigned tg = og / nx;
;             if (og + 1u == (tg + 1u) * nx) xb_add(&bar[XB_TOPGEN], 1u);
;             else XB_SPIN(xb_ld(&bar[XB_TOPGEN]) == tg, bar);
;             __builtin_amdgcn_fence(__ATOMIC_ACQUIRE, "agent");
;             xb_add(&bar[XB_XGEN(b.x)], 1u);
;             asm volatile("s_waitcnt vmcnt(0)" ::: "memory");
;         } else {
;             XB_SPIN(xb_ld(&bar[XB_XGEN(b.x)]) == gen, bar);
;             __builtin_amdgcn_fence(__ATOMIC_ACQUIRE, "agent");
;             asm volatile("s_waitcnt vmcnt(0)" ::: "memory");
;         }
.LBB0_100:
	s_mov_b32 s2, 0x27ff0
	s_mov_b32 s3, 0x27ff4
	v_readlane_b32 s12, v254, 41
	v_readlane_b32 s13, v254, 42
	s_waitcnt lgkmcnt(0)
	v_mov_b32_e32 v0, s2
	v_mov_b32_e32 v4, s3
	ds_read_b32 v3, v0
	ds_read_b32 v2, v4
	v_mov_b32_e32 v5, 0
	v_mov_b32_e32 v6, 1
	s_nop 1
	global_atomic_add v6, v5, v6, s[12:13] sc0
	v_readlane_b32 s2, v254, 45
	v_readlane_b32 s3, v254, 46
	s_waitcnt vmcnt(0) lgkmcnt(0)
	v_cvt_f32_u32_e32 v0, v3
	v_sub_u32_e32 v4, 0, v3
	v_rcp_iflag_f32_e32 v0, v0
	s_nop 0
	v_mul_f32_e32 v0, 0x4f7ffffe, v0
	v_cvt_u32_f32_e32 v0, v0
	v_mul_lo_u32 v4, v4, v0
	v_mul_hi_u32 v4, v0, v4
	v_add_u32_e32 v0, v0, v4
	v_mul_hi_u32 v0, v6, v0
	v_mul_lo_u32 v4, v0, v3
	v_sub_u32_e32 v4, v6, v4
	v_add_u32_e32 v7, 1, v0
	v_cmp_ge_u32_e32 vcc, v4, v3
	s_nop 1
	v_cndmask_b32_e32 v0, v0, v7, vcc
	v_sub_u32_e32 v7, v4, v3
	v_cndmask_b32_e32 v4, v4, v7, vcc
	v_add_u32_e32 v7, 1, v0
	v_cmp_ge_u32_e32 vcc, v4, v3
	s_nop 1
	v_cndmask_b32_e32 v0, v0, v7, vcc
	v_add_u32_e32 v7, 1, v0
	v_mul_lo_u32 v4, v7, v3
	v_mul_lo_u32 v7, v7, v2
	v_add_u32_e32 v6, 1, v6
	v_cmp_ne_u32_e32 vcc, v6, v4
	s_mov_b32 s98, 0
	s_cbranch_vccnz .Lxb0_early
	buffer_wbl2 sc1
	buffer_inv sc1
	s_waitcnt vmcnt(0)
	v_mov_b32_e32 v6, 1
	global_atomic_add v5, v6, s[2:3]
	s_branch .Lxb0_poll
.Lxb0_early:
	buffer_inv sc1
.Lxb0_poll:
	global_load_dword v6, v5, s[2:3] sc1
	s_waitcnt vmcnt(0)
	v_cmp_lt_u32_e32 vcc, v6, v7
	s_cbranch_vccz .Lxb0_done
	s_sleep 1
	s_add_i32 s98, s98, 1
	s_cmp_lt_u32 s98, 0x40000
	s_cbranch_scc1 .Lxb0_poll
.Lxb0_done:
	s_nop 0
	s_waitcnt vmcnt(0)

; __device__ __forceinline__ unsigned xb_ld(unsigned* p)              { return __hip_atomic_load(p, __ATOMIC_RELAXED, __HIP_MEMORY_SCOPE_AGENT); }
; __device__ __forceinline__ unsigned xb_add(unsigned* p, unsigned v) { return __hip_atomic_fetch_add(p, v, __ATOMIC_RELAXED, __HIP_MEMORY_SCOPE_AGENT); }
; #define XB_SPIN(cond, bar) do { unsigned _sp = 0; while (cond) { __builtin_amdgcn_s_sleep(1); \
;     if ((++_sp & 255u) == 0u) { if (xb_ld(&(bar)[XB_TMO])) break; if (_sp > XB_SPIN_CAP) { atomicAdd(&(bar)[XB_TMO], 1u); break; } } } } while (0)
; __device__ __forceinline__ void xcd_barrier(const XcdBarrier& b) {
;     ...
;         unsigned nloc = b.st[0], nx = b.st[1];
;         if (nloc == 0u) { xcd_barrier_complete(bar, b.x, nloc, nx); b.st[0] = nloc; b.st[1] = nx; }
;         const unsigned old = xb_add(&bar[XB_XSUB(b.x)], 1u);
;         const unsigned gen = old / nloc;
;         if (old + 1u == (gen + 1u) * nloc) {
;             __builtin_amdgcn_fence(__ATOMIC_RELEASE, "agent");
;             asm volatile("s_waitcnt vmcnt(0)" ::: "memory");
;             const unsigned og = xb_add(&bar[XB_TOP], 1u);
;             const unsigned tg = og / nx;
;             if (og + 1u == (tg + 1u) * nx) xb_add(&bar[XB_TOPGEN], 1u);
;             else XB_SPIN(xb_ld(&bar[XB_TOPGEN]) == tg, bar);
;             __builtin_amdgcn_fence(__ATOMIC_ACQUIRE, "agent");
;             xb_add(&bar[XB_XGEN(b.x)], 1u);
;             asm volatile("s_waitcnt vmcnt(0)" ::: "memory");
;         } else {
;             XB_SPIN(xb_ld(&bar[XB_XGEN(b.x)]) == gen, bar);
;             __builtin_amdgcn_fence(__ATOMIC_ACQUIRE, "agent");
;             asm volatile("s_waitcnt vmcnt(0)" ::: "memory");
;         }
.LBB0_469:
	v_readlane_b32 s2, v254, 59
	v_readlane_b32 s3, v254, 60
	v_readlane_b32 s12, v254, 41
	v_readlane_b32 s13, v254, 42
	s_waitcnt lgkmcnt(0)
	v_mov_b32_e32 v0, s2
	v_mov_b32_e32 v4, s3
	ds_read_b32 v3, v0
	ds_read_b32 v2, v4
	v_mov_b32_e32 v5, 0
	v_mov_b32_e32 v6, 1
	s_nop 1
	global_atomic_add v6, v5, v6, s[12:13] sc0
	v_readlane_b32 s2, v254, 45
	v_readlane_b32 s3, v254, 46
	s_waitcnt vmcnt(0) lgkmcnt(0)
	v_cvt_f32_u32_e32 v0, v3
	v_sub_u32_e32 v4, 0, v3
	v_rcp_iflag_f32_e32 v0, v0
	s_nop 0
	v_mul_f32_e32 v0, 0x4f7ffffe, v0
	v_cvt_u32_f32_e32 v0, v0
	v_mul_lo_u32 v4, v4, v0
	v_mul_hi_u32 v4, v0, v4
	v_add_u32_e32 v0, v0, v4
	v_mul_hi_u32 v0, v6, v0
	v_mul_lo_u32 v4, v0, v3
	v_sub_u32_e32 v4, v6, v4
	v_add_u32_e32 v7, 1, v0
	v_cmp_ge_u32_e32 vcc, v4, v3
	s_nop 1
	v_cndmask_b32_e32 v0, v0, v7, vcc
	v_sub_u32_e32 v7, v4, v3
	v_cndmask_b32_e32 v4, v4, v7, vcc
	v_add_u32_e32 v7, 1, v0
	v_cmp_ge_u32_e32 vcc, v4, v3
	s_nop 1
	v_cndmask_b32_e32 v0, v0, v7, vcc
	v_add_u32_e32 v7, 1, v0
	v_mul_lo_u32 v4, v7, v3
	v_mul_lo_u32 v7, v7, v2
	v_add_u32_e32 v6, 1, v6
	v_cmp_ne_u32_e32 vcc, v6, v4
	s_mov_b32 s98, 0
	s_cbranch_vccnz .Lxb1_early
	buffer_wbl2 sc1
	buffer_inv sc1
	s_waitcnt vmcnt(0)
	v_mov_b32_e32 v6, 1
	global_atomic_add v5, v6, s[2:3]
	s_branch .Lxb1_poll
.Lxb1_early:
	buffer_inv sc1
.Lxb1_poll:
	global_load_dword v6, v5, s[2:3] sc1
	s_waitcnt vmcnt(0)
	v_cmp_lt_u32_e32 vcc, v6, v7
	s_cbranch_vccz .Lxb1_done
	s_sleep 1
	s_add_i32 s98, s98, 1
	s_cmp_lt_u32 s98, 0x40000
	s_cbranch_scc1 .Lxb1_poll

; __device__ __forceinline__ unsigned xb_ld(unsigned* p)              { return __hip_atomic_load(p, __ATOMIC_RELAXED, __HIP_MEMORY_SCOPE_AGENT); }
; __device__ __forceinline__ unsigned xb_add(unsigned* p, unsigned v) { return __hip_atomic_fetch_add(p, v, __ATOMIC_RELAXED, __HIP_MEMORY_SCOPE_AGENT); }
; #define XB_SPIN(cond, bar) do { unsigned _sp = 0; while (cond) { __builtin_amdgcn_s_sleep(1); \
;     if ((++_sp & 255u) == 0u) { if (xb_ld(&(bar)[XB_TMO])) break; if (_sp > XB_SPIN_CAP) { atomicAdd(&(bar)[XB_TMO], 1u); break; } } } } while (0)
; __device__ __forceinline__ void xcd_barrier(const XcdBarrier& b) {
;     ...
;             else XB_SPIN(xb_ld(&bar[XB_TOPGEN]) == tg, bar);
;             __builtin_amdgcn_fence(__ATOMIC_ACQUIRE, "agent");
;             xb_add(&bar[XB_XGEN(b.x)], 1u);
;             asm volatile("s_waitcnt vmcnt(0)" ::: "memory");
;         } else {
;             XB_SPIN(xb_ld(&bar[XB_XGEN(b.x)]) == gen, bar);
;             __builtin_amdgcn_fence(__ATOMIC_ACQUIRE, "agent");
;             asm volatile("s_waitcnt vmcnt(0)" ::: "memory");
.Lxb2_early:
	buffer_inv sc1
.Lxb2_poll:
	global_load_dword v6, v5, s[2:3] sc1
	s_waitcnt vmcnt(0)
	v_cmp_lt_u32_e32 vcc, v6, v7
	s_cbranch_vccz .Lxb2_done
	s_sleep 1
	s_add_i32 s98, s98, 1
	s_cmp_lt_u32 s98, 0x40000
	s_cbranch_scc1 .Lxb2_poll

; __device__ __forceinline__ unsigned xb_ld(unsigned* p)              { return __hip_atomic_load(p, __ATOMIC_RELAXED, __HIP_MEMORY_SCOPE_AGENT); }
; __device__ __forceinline__ unsigned xb_add(unsigned* p, unsigned v) { return __hip_atomic_fetch_add(p, v, __ATOMIC_RELAXED, __HIP_MEMORY_SCOPE_AGENT); }
; #define XB_SPIN(cond, bar) do { unsigned _sp = 0; while (cond) { __builtin_amdgcn_s_sleep(1); \
;     if ((++_sp & 255u) == 0u) { if (xb_ld(&(bar)[XB_TMO])) break; if (_sp > XB_SPIN_CAP) { atomicAdd(&(bar)[XB_TMO], 1u); break; } } } } while (0)
; __device__ __forceinline__ void xcd_barrier(const XcdBarrier& b) {
;     ...
;             else XB_SPIN(xb_ld(&bar[XB_TOPGEN]) == tg, bar);
;             __builtin_amdgcn_fence(__ATOMIC_ACQUIRE, "agent");
;             xb_add(&bar[XB_XGEN(b.x)], 1u);
;             asm volatile("s_waitcnt vmcnt(0)" ::: "memory");
;         } else {
;             XB_SPIN(xb_ld(&bar[XB_XGEN(b.x)]) == gen, bar);
;             __builtin_amdgcn_fence(__ATOMIC_ACQUIRE, "agent");
;             asm volatile("s_waitcnt vmcnt(0)" ::: "memory");
.Lxb3_early:
	buffer_inv sc1
.Lxb3_poll:
	global_load_dword v6, v5, s[2:3] sc1
	s_waitcnt vmcnt(0)
	v_cmp_lt_u32_e32 vcc, v6, v7
	s_cbranch_vccz .Lxb3_done
	s_sleep 1
	s_add_i32 s98, s98, 1
	s_cmp_lt_u32 s98, 0x40000
	s_cbranch_scc1 .Lxb3_poll

; __device__ __forceinline__ unsigned xb_ld(unsigned* p)              { return __hip_atomic_load(p, __ATOMIC_RELAXED, __HIP_MEMORY_SCOPE_AGENT); }
; __device__ __forceinline__ unsigned xb_add(unsigned* p, unsigned v) { return __hip_atomic_fetch_add(p, v, __ATOMIC_RELAXED, __HIP_MEMORY_SCOPE_AGENT); }
; #define XB_SPIN(cond, bar) do { unsigned _sp = 0; while (cond) { __builtin_amdgcn_s_sleep(1); \
;     if ((++_sp & 255u) == 0u) { if (xb_ld(&(bar)[XB_TMO])) break; if (_sp > XB_SPIN_CAP) { atomicAdd(&(bar)[XB_TMO], 1u); break; } } } } while (0)
; __device__ __forceinline__ void xcd_barrier(const XcdBarrier& b) {
;     ...
;             else XB_SPIN(xb_ld(&bar[XB_TOPGEN]) == tg, bar);
;             __builtin_amdgcn_fence(__ATOMIC_ACQUIRE, "agent");
;             xb_add(&bar[XB_XGEN(b.x)], 1u);
;             asm volatile("s_waitcnt vmcnt(0)" ::: "memory");
;         } else {
;             XB_SPIN(xb_ld(&bar[XB_XGEN(b.x)]) == gen, bar);
;             __builtin_amdgcn_fence(__ATOMIC_ACQUIRE, "agent");
;             asm volatile("s_waitcnt vmcnt(0)" ::: "memory");
.Lxb4_early:
	buffer_inv sc1
.Lxb4_poll:
	global_load_dword v6, v5, s[2:3] sc1
	s_waitcnt vmcnt(0)
	v_cmp_lt_u32_e32 vcc, v6, v7
	s_cbranch_vccz .Lxb4_done
	s_sleep 1
	s_add_i32 s98, s98, 1
	s_cmp_lt_u32 s98, 0x40000
	s_cbranch_scc1 .Lxb4_poll

; __device__ __forceinline__ unsigned xb_ld(unsigned* p)              { return __hip_atomic_load(p, __ATOMIC_RELAXED, __HIP_MEMORY_SCOPE_AGENT); }
; __device__ __forceinline__ unsigned xb_add(unsigned* p, unsigned v) { return __hip_atomic_fetch_add(p, v, __ATOMIC_RELAXED, __HIP_MEMORY_SCOPE_AGENT); }
; #define XB_SPIN(cond, bar) do { unsigned _sp = 0; while (cond) { __builtin_amdgcn_s_sleep(1); \
;     if ((++_sp & 255u) == 0u) { if (xb_ld(&(bar)[XB_TMO])) break; if (_sp > XB_SPIN_CAP) { atomicAdd(&(bar)[XB_TMO], 1u); break; } } } } while (0)
; __device__ __forceinline__ void xcd_barrier(const XcdBarrier& b) {
;     ...
;             else XB_SPIN(xb_ld(&bar[XB_TOPGEN]) == tg, bar);
;             __builtin_amdgcn_fence(__ATOMIC_ACQUIRE, "agent");
;             xb_add(&bar[XB_XGEN(b.x)], 1u);
;             asm volatile("s_waitcnt vmcnt(0)" ::: "memory");
;         } else {
;             XB_SPIN(xb_ld(&bar[XB_XGEN(b.x)]) == gen, bar);
;             __builtin_amdgcn_fence(__ATOMIC_ACQUIRE, "agent");
;             asm volatile("s_waitcnt vmcnt(0)" ::: "memory");
.Lxb5_early:
	buffer_inv sc1
.Lxb5_poll:
	global_load_dword v6, v5, s[2:3] sc1
	s_waitcnt vmcnt(0)
	v_cmp_lt_u32_e32 vcc, v6, v7
	s_cbranch_vccz .Lxb5_done
	s_sleep 1
	s_add_i32 s98, s98, 1
	s_cmp_lt_u32 s98, 0x40000
	s_cbranch_scc1 .Lxb5_poll

; __device__ __forceinline__ unsigned xb_ld(unsigned* p)              { return __hip_atomic_load(p, __ATOMIC_RELAXED, __HIP_MEMORY_SCOPE_AGENT); }
; __device__ __forceinline__ unsigned xb_add(unsigned* p, unsigned v) { return __hip_atomic_fetch_add(p, v, __ATOMIC_RELAXED, __HIP_MEMORY_SCOPE_AGENT); }
; #define XB_SPIN(cond, bar) do { unsigned _sp = 0; while (cond) { __builtin_amdgcn_s_sleep(1); \
;     if ((++_sp & 255u) == 0u) { if (xb_ld(&(bar)[XB_TMO])) break; if (_sp > XB_SPIN_CAP) { atomicAdd(&(bar)[XB_TMO], 1u); break; } } } } while (0)
; __device__ __forceinline__ void xcd_barrier(const XcdBarrier& b) {
;     ...
;             else XB_SPIN(xb_ld(&bar[XB_TOPGEN]) == tg, bar);
;             __builtin_amdgcn_fence(__ATOMIC_ACQUIRE, "agent");
;             xb_add(&bar[XB_XGEN(b.x)], 1u);
;             asm volatile("s_waitcnt vmcnt(0)" ::: "memory");
;         } else {
;             XB_SPIN(xb_ld(&bar[XB_XGEN(b.x)]) == gen, bar);
;             __builtin_amdgcn_fence(__ATOMIC_ACQUIRE, "agent");
;             asm volatile("s_waitcnt vmcnt(0)" ::: "memory");
.Lxb6_early:
	buffer_inv sc1
.Lxb6_poll:
	global_load_dword v6, v5, s[2:3] sc1
	s_waitcnt vmcnt(0)
	v_cmp_lt_u32_e32 vcc, v6, v7
	s_cbranch_vccz .Lxb6_done
	s_sleep 1
	s_add_i32 s98, s98, 1
	s_cmp_lt_u32 s98, 0x40000
	s_cbranch_scc1 .Lxb6_poll

; __device__ __forceinline__ unsigned xb_ld(unsigned* p)              { return __hip_atomic_load(p, __ATOMIC_RELAXED, __HIP_MEMORY_SCOPE_AGENT); }
; __device__ __forceinline__ unsigned xb_add(unsigned* p, unsigned v) { return __hip_atomic_fetch_add(p, v, __ATOMIC_RELAXED, __HIP_MEMORY_SCOPE_AGENT); }
; #define XB_SPIN(cond, bar) do { unsigned _sp = 0; while (cond) { __builtin_amdgcn_s_sleep(1); \
;     if ((++_sp & 255u) == 0u) { if (xb_ld(&(bar)[XB_TMO])) break; if (_sp > XB_SPIN_CAP) { atomicAdd(&(bar)[XB_TMO], 1u); break; } } } } while (0)
; __device__ __forceinline__ void xcd_barrier(const XcdBarrier& b) {
;     ...
;             else XB_SPIN(xb_ld(&bar[XB_TOPGEN]) == tg, bar);
;             __builtin_amdgcn_fence(__ATOMIC_ACQUIRE, "agent");
;             xb_add(&bar[XB_XGEN(b.x)], 1u);
;             asm volatile("s_waitcnt vmcnt(0)" ::: "memory");
;         } else {
;             XB_SPIN(xb_ld(&bar[XB_XGEN(b.x)]) == gen, bar);
;             __builtin_amdgcn_fence(__ATOMIC_ACQUIRE, "agent");
;             asm volatile("s_waitcnt vmcnt(0)" ::: "memory");
.Lxb7_early:
	buffer_inv sc1
.Lxb7_poll:
	global_load_dword v6, v5, s[2:3] sc1
	s_waitcnt vmcnt(0)
	v_cmp_lt_u32_e32 vcc, v6, v7
	s_cbranch_vccz .Lxb7_done
	s_sleep 1
	s_add_i32 s98, s98, 1
	s_cmp_lt_u32 s98, 0x40000
	s_cbranch_scc1 .Lxb7_poll

; __device__ __forceinline__ unsigned xb_ld(unsigned* p)              { return __hip_atomic_load(p, __ATOMIC_RELAXED, __HIP_MEMORY_SCOPE_AGENT); }
; __device__ __forceinline__ unsigned xb_add(unsigned* p, unsigned v) { return __hip_atomic_fetch_add(p, v, __ATOMIC_RELAXED, __HIP_MEMORY_SCOPE_AGENT); }
; #define XB_SPIN(cond, bar) do { unsigned _sp = 0; while (cond) { __builtin_amdgcn_s_sleep(1); \
;     if ((++_sp & 255u) == 0u) { if (xb_ld(&(bar)[XB_TMO])) break; if (_sp > XB_SPIN_CAP) { atomicAdd(&(bar)[XB_TMO], 1u); break; } } } } while (0)
; __device__ __forceinline__ void xcd_barrier(const XcdBarrier& b) {
;     ...
;             else XB_SPIN(xb_ld(&bar[XB_TOPGEN]) == tg, bar);
;             __builtin_amdgcn_fence(__ATOMIC_ACQUIRE, "agent");
;             xb_add(&bar[XB_XGEN(b.x)], 1u);
;             asm volatile("s_waitcnt vmcnt(0)" ::: "memory");
;         } else {
;             XB_SPIN(xb_ld(&bar[XB_XGEN(b.x)]) == gen, bar);
;             __builtin_amdgcn_fence(__ATOMIC_ACQUIRE, "agent");
;             asm volatile("s_waitcnt vmcnt(0)" ::: "memory");
.Lxb8_early:
	buffer_inv sc1
.Lxb8_poll:
	global_load_dword v6, v5, s[2:3] sc1
	s_waitcnt vmcnt(0)
	v_cmp_lt_u32_e32 vcc, v6, v7
	s_cbranch_vccz .Lxb8_done
	s_sleep 1
	s_add_i32 s98, s98, 1
	s_cmp_lt_u32 s98, 0x40000
	s_cbranch_scc1 .Lxb8_poll

; __device__ __forceinline__ unsigned xb_ld(unsigned* p)              { return __hip_atomic_load(p, __ATOMIC_RELAXED, __HIP_MEMORY_SCOPE_AGENT); }
; __device__ __forceinline__ unsigned xb_add(unsigned* p, unsigned v) { return __hip_atomic_fetch_add(p, v, __ATOMIC_RELAXED, __HIP_MEMORY_SCOPE_AGENT); }
; #define XB_SPIN(cond, bar) do { unsigned _sp = 0; while (cond) { __builtin_amdgcn_s_sleep(1); \
;     if ((++_sp & 255u) == 0u) { if (xb_ld(&(bar)[XB_TMO])) break; if (_sp > XB_SPIN_CAP) { atomicAdd(&(bar)[XB_TMO], 1u); break; } } } } while (0)
; __device__ __forceinline__ void xcd_barrier(const XcdBarrier& b) {
;     ...
;             else XB_SPIN(xb_ld(&bar[XB_TOPGEN]) == tg, bar);
;             __builtin_amdgcn_fence(__ATOMIC_ACQUIRE, "agent");
;             xb_add(&bar[XB_XGEN(b.x)], 1u);
;             asm volatile("s_waitcnt vmcnt(0)" ::: "memory");
;         } else {
;             XB_SPIN(xb_ld(&bar[XB_XGEN(b.x)]) == gen, bar);
;             __builtin_amdgcn_fence(__ATOMIC_ACQUIRE, "agent");
;             asm volatile("s_waitcnt vmcnt(0)" ::: "memory");
.Lxb9_early:
	buffer_inv sc1
.Lxb9_poll:
	global_load_dword v6, v5, s[2:3] sc1
	s_waitcnt vmcnt(0)
	v_cmp_lt_u32_e32 vcc, v6, v7
	s_cbranch_vccz .Lxb9_done
	s_sleep 1
	s_add_i32 s98, s98, 1
	s_cmp_lt_u32 s98, 0x40000
	s_cbranch_scc1 .Lxb9_poll

; __device__ __forceinline__ unsigned xb_ld(unsigned* p)              { return __hip_atomic_load(p, __ATOMIC_RELAXED, __HIP_MEMORY_SCOPE_AGENT); }
; #define XB_SPIN(cond, bar) do { unsigned _sp = 0; while (cond) { __builtin_amdgcn_s_sleep(1); \
;     if ((++_sp & 255u) == 0u) { if (xb_ld(&(bar)[XB_TMO])) break; if (_sp > XB_SPIN_CAP) { atomicAdd(&(bar)[XB_TMO], 1u); break; } } } } while (0)
; __device__ __forceinline__ void xcd_barrier(const XcdBarrier& b) {
;     ...
;             XB_SPIN(xb_ld(&bar[XB_XGEN(b.x)]) == gen, bar);
;             __builtin_amdgcn_fence(__ATOMIC_ACQUIRE, "agent");
;             asm volatile("s_waitcnt vmcnt(0)" ::: "memory");
.Lxb10_early:
	buffer_inv sc1
.Lxb10_poll:
	global_load_dword v6, v5, s[2:3] sc1
	s_waitcnt vmcnt(0)
	v_cmp_lt_u32_e32 vcc, v6, v7
	s_cbranch_vccz .Lxb10_done
	s_sleep 1
	s_add_i32 s98, s98, 1
	s_cmp_lt_u32 s98, 0x40000
	s_cbranch_scc1 .Lxb10_poll
.Lxb10_done:
	s_nop 0
	s_waitcnt vmcnt(0)
	s_mov_b64 s[12:13], exec
	s_getpc_b64 s[98:99]
